# P4 epilogue rotated-key path: rope frequencies loaded once at the top, no per-row-group drain
# speedup vs baseline: 1.0002x; 1.0002x over previous
.LBB0_331:
	v_lshl_add_u32 v154, s8, 8, v1
	v_ashrrev_i32_e32 v155, 31, v154
	v_lshlrev_b64 v[156:157], 6, v[154:155]
	v_lshl_add_u64 v[156:157], s[30:31], 0, v[156:157]
	v_and_b32_e32 v250, 16, v0
	v_lshrrev_b32_e32 v251, 1, v250
	v_add_u32_e32 v250, v250, v251
	v_mov_b32_e32 v251, 0
	v_mov_b32_e32 v242, v156
	v_mov_b32_e32 v243, v157
	v_mov_b32_e32 v244, 0x2000
	v_mov_b32_e32 v245, 0
	v_lshl_add_u64 v[244:245], v[156:157], 0, v[244:245]
	global_load_dwordx4 v[246:249], v[138:139], off
	global_load_dwordx4 v[166:169], v[156:157], off
	global_load_dwordx4 v[170:173], v[156:157], off offset:16
	global_load_dwordx4 v[174:177], v[156:157], off offset:32
	global_load_dwordx4 v[178:181], v[156:157], off offset:48
	global_load_dwordx4 v[194:197], v[242:243], off offset:1024
	global_load_dwordx4 v[198:201], v[242:243], off offset:1040
	global_load_dwordx4 v[202:205], v[242:243], off offset:1056
	global_load_dwordx4 v[206:209], v[242:243], off offset:1072
	global_load_dwordx4 v[210:213], v[242:243], off offset:2048
	global_load_dwordx4 v[214:217], v[242:243], off offset:2064
	global_load_dwordx4 v[218:221], v[242:243], off offset:2080
	global_load_dwordx4 v[222:225], v[242:243], off offset:2096
	global_load_dwordx4 v[226:229], v[242:243], off offset:3072
	global_load_dwordx4 v[230:233], v[242:243], off offset:3088
	global_load_dwordx4 v[234:237], v[242:243], off offset:3104
	global_load_dwordx4 v[238:241], v[242:243], off offset:3120
	s_cmp_gt_i32 s18, 3
	s_cselect_b64 s[20:21], -1, 0
	s_cmp_lg_u32 s18, 4
	s_cselect_b64 s[22:23], -1, 0
	s_cmp_lt_i32 s18, 2
	s_cselect_b64 s[84:85], -1, 0
	s_cmp_gt_i32 s18, 1
	s_mov_b64 s[8:9], -1
	s_cselect_b64 s[38:39], -1, 0
	s_and_b64 vcc, exec, s[20:21]
	s_waitcnt vmcnt(12)
	v_pk_add_f32 v[156:157], v[168:169], v[172:173]
	v_pk_add_f32 v[166:167], v[166:167], v[170:171]
	v_pk_add_f32 v[168:169], v[176:177], v[180:181]
	v_pk_add_f32 v[170:171], v[174:175], v[178:179]
	v_pk_add_f32 v[156:157], v[156:157], v[168:169]
	v_pk_add_f32 v[166:167], v[166:167], v[170:171]
	s_nop 0
	v_pk_mov_b32 v[168:169], v[166:167], v[156:157] op_sel:[1,0]
	v_mov_b32_e32 v167, v157
	v_pk_add_f32 v[156:157], v[168:169], v[166:167]
	s_nop 0
	v_add_f32_e32 v134, v156, v157
	v_fmamk_f32 v134, v134, 0x3a800000, v162
	v_rsq_f32_e32 v134, v134
	s_nop 0
	v_pk_mul_f32 v[128:129], v[128:129], v[134:135] op_sel_hi:[1,0]
	v_pk_mul_f32 v[126:127], v[126:127], v[134:135] op_sel_hi:[1,0]
	v_pk_mul_f32 v[124:125], v[124:125], v[134:135] op_sel_hi:[1,0]
	v_pk_mul_f32 v[122:123], v[122:123], v[134:135] op_sel_hi:[1,0]
	v_pk_mul_f32 v[120:121], v[120:121], v[134:135] op_sel_hi:[1,0]
	v_pk_mul_f32 v[118:119], v[118:119], v[134:135] op_sel_hi:[1,0]
	v_pk_mul_f32 v[116:117], v[116:117], v[134:135] op_sel_hi:[1,0]
	v_pk_mul_f32 v[114:115], v[114:115], v[134:135] op_sel_hi:[1,0]
	s_cbranch_vccz .LBB0_343
	v_mul_f32_e32 v134, v127, v127
	v_mul_f32_e32 v156, v129, v129
	v_fmac_f32_e32 v134, v126, v126
	v_fmac_f32_e32 v156, v128, v128
	v_add_f32_e32 v166, v134, v156
	s_and_b64 vcc, exec, s[22:23]
	v_lshlrev_b64 v[156:157], 9, v[154:155]
	v_mul_f32_e32 v167, v123, v123
	v_mul_f32_e32 v168, v125, v125
	s_cbranch_vccz .LBB0_338
	v_fma_f32 v134, v122, v122, v167
	v_fma_f32 v169, v124, v124, v168
	v_and_b32_e32 v173, 64, v163
	v_add_f32_e32 v134, v134, v169
	v_xor_b32_e32 v169, 16, v163
	v_add_u32_e32 v176, 64, v173
	v_cmp_lt_i32_e32 vcc, v169, v176
	v_add_f32_e32 v134, v166, v134
	v_lshlrev_b64 v[174:175], 8, v[154:155]
	v_cndmask_b32_e32 v169, v163, v169, vcc
	v_lshlrev_b32_e32 v169, 2, v169
	ds_bpermute_b32 v169, v169, v134
	v_lshl_add_u64 v[170:171], v[140:141], 0, v[156:157]
	v_lshl_add_u64 v[174:175], v[142:143], 0, v[174:175]
	global_store_dwordx4 v[170:171], v[126:129], off
	v_cvt_pk_bf16_f32 v172, v126, v127
	s_waitcnt lgkmcnt(0)
	v_add_f32_e32 v134, v134, v169
	v_xor_b32_e32 v169, 32, v163
	v_cmp_lt_i32_e32 vcc, v169, v176
	v_cvt_pk_bf16_f32 v173, v128, v129
	global_store_dwordx2 v[174:175], v[172:173], off
	global_store_dwordx4 v[170:171], v[122:125], off offset:64
	v_cndmask_b32_e32 v169, v163, v169, vcc
	v_lshlrev_b32_e32 v169, 2, v169
	ds_bpermute_b32 v169, v169, v134
	v_cvt_pk_bf16_f32 v170, v122, v123
	v_cvt_pk_bf16_f32 v171, v124, v125
	global_store_dwordx2 v[174:175], v[170:171], off offset:32
	s_and_saveexec_b64 s[8:9], s[4:5]
	s_cbranch_execz .LBB0_335
	v_lshlrev_b64 v[170:171], 5, v[154:155]
	v_lshl_add_u64 v[170:171], s[42:43], 0, v[170:171]
	s_waitcnt lgkmcnt(0)
	v_add_f32_e32 v134, v134, v169
	global_store_dword v[170:171], v134, off offset:16
.LBB0_335:
	s_or_b64 exec, exec, s[8:9]
	s_andn2_b64 vcc, exec, s[40:41]
	s_cbranch_vccnz .LBB0_337
	v_mov_b32_e32 v170, v246
	v_mov_b32_e32 v171, v247
	v_mov_b32_e32 v172, v248
	v_mov_b32_e32 v173, v249
	v_readlane_b32 s8, v255, 0
	s_waitcnt lgkmcnt(0)
	v_and_b32_e32 v169, 0x1fcf, v154
	v_cmp_gt_i32_e32 vcc, s77, v154
	v_readlane_b32 s9, v255, 1
	v_add_u32_e32 v134, 0xffffc000, v154
	v_cndmask_b32_e32 v169, v158, v169, vcc
	s_load_dwordx4 s[0:3], s[8:9], 0x108
	v_lshlrev_b64 v[182:183], 7, v[134:135]
	v_cndmask_b32_e32 v184, v134, v154, vcc
	v_cvt_f32_u32_e32 v134, v169
	v_lshlrev_b64 v[174:175], 7, v[154:155]
	v_mov_b32_e32 v177, v135
	v_cndmask_b32_e32 v176, v164, v165, vcc
	v_lshl_add_u64 v[174:175], s[46:47], 0, v[174:175]
	v_lshl_add_u64 v[182:183], s[44:45], 0, v[182:183]
	s_waitcnt lgkmcnt(0)
	v_lshl_add_u64 v[176:177], s[2:3], 0, v[176:177]
	v_cndmask_b32_e32 v186, 0, v155, vcc
	v_cndmask_b32_e32 v183, v183, v175, vcc
	v_cndmask_b32_e32 v182, v182, v174, vcc
	v_mad_u64_u32 v[184:185], s[0:1], v184, s95, v[176:177]
	v_mad_i32_i24 v185, v186, s95, v185
	v_mov_b64_e32 v[178:179], s[54:55]
	v_mov_b64_e32 v[180:181], s[62:63]
	v_pk_mul_f32 v[170:171], v[170:171], v[134:135] op_sel_hi:[1,0]
	v_pk_mul_f32 v[172:173], v[172:173], v[134:135] op_sel_hi:[1,0]
	v_cvt_f64_f32_e32 v[174:175], v170
	v_cvt_f64_f32_e32 v[170:171], v171
	v_cvt_f64_f32_e32 v[176:177], v172
	v_cvt_f64_f32_e32 v[172:173], v173
	v_mul_f64 v[186:187], v[170:171], s[48:49]
	v_mul_f64 v[188:189], v[174:175], s[48:49]
	v_mul_f64 v[190:191], v[172:173], s[48:49]
	v_mul_f64 v[192:193], v[176:177], s[48:49]
	v_rndne_f64_e32 v[188:189], v[188:189]
	v_rndne_f64_e32 v[186:187], v[186:187]
	v_rndne_f64_e32 v[192:193], v[192:193]
	v_rndne_f64_e32 v[190:191], v[190:191]
	v_fma_f64 v[170:171], v[170:171], s[48:49], -v[186:187]
	v_fma_f64 v[174:175], v[174:175], s[48:49], -v[188:189]
	v_fma_f64 v[172:173], v[172:173], s[48:49], -v[190:191]
	v_fma_f64 v[176:177], v[176:177], s[48:49], -v[192:193]
	v_mul_f64 v[174:175], v[174:175], s[50:51]
	v_mul_f64 v[170:171], v[170:171], s[50:51]
	v_mul_f64 v[176:177], v[176:177], s[50:51]
	v_mul_f64 v[172:173], v[172:173], s[50:51]
	v_cvt_f32_f64_e32 v171, v[170:171]
	v_cvt_f32_f64_e32 v170, v[174:175]
	v_cvt_i32_f64_e32 v134, v[186:187]
	v_cvt_i32_f64_e32 v186, v[190:191]
	v_cvt_i32_f64_e32 v187, v[192:193]
	v_cvt_f32_f64_e32 v173, v[172:173]
	v_cvt_f32_f64_e32 v172, v[176:177]
	v_pk_mul_f32 v[174:175], v[170:171], v[170:171]
	v_cvt_i32_f64_e32 v169, v[188:189]
	v_and_b32_e32 v190, 3, v186
	v_and_b32_e32 v191, 3, v187
	v_pk_mul_f32 v[176:177], v[172:173], v[172:173]
	v_pk_fma_f32 v[186:187], v[174:175], s[52:53], v[178:179] op_sel_hi:[1,0,0]
	v_pk_fma_f32 v[188:189], v[174:175], s[60:61], v[180:181] op_sel_hi:[1,0,0] neg_lo:[1,0,0] neg_hi:[1,0,0]
	v_pk_fma_f32 v[178:179], v[176:177], s[52:53], v[178:179] op_sel_hi:[1,0,0]
	v_pk_fma_f32 v[186:187], v[174:175], v[186:187], s[56:57] op_sel_hi:[1,1,0]
	v_pk_fma_f32 v[188:189], v[174:175], v[188:189], s[64:65] op_sel_hi:[1,1,0]
	v_pk_fma_f32 v[178:179], v[176:177], v[178:179], s[56:57] op_sel_hi:[1,1,0]
	v_pk_fma_f32 v[186:187], v[174:175], v[186:187], s[58:59] op_sel_hi:[1,1,0]
	v_pk_fma_f32 v[188:189], v[174:175], v[188:189], s[66:67] op_sel_hi:[1,1,0]
	v_and_b32_e32 v134, 3, v134
	v_and_b32_e32 v169, 3, v169
	v_pk_fma_f32 v[178:179], v[176:177], v[178:179], s[58:59] op_sel_hi:[1,1,0]
	v_pk_fma_f32 v[186:187], v[174:175], v[186:187], 1.0 op_sel_hi:[1,1,0]
	v_pk_fma_f32 v[188:189], v[174:175], v[188:189], -0.5 op_sel_hi:[1,1,0]
	v_pk_fma_f32 v[178:179], v[176:177], v[178:179], 1.0 op_sel_hi:[1,1,0]
	v_pk_mul_f32 v[170:171], v[186:187], v[170:171]
	v_pk_fma_f32 v[174:175], v[174:175], v[188:189], 1.0 op_sel_hi:[1,1,0]
	v_cmp_eq_u32_e32 vcc, 2, v134
	v_cmp_eq_u32_e64 s[8:9], 2, v169
	v_pk_mul_f32 v[172:173], v[178:179], v[172:173]
	v_cndmask_b32_e64 v178, v171, -v175, vcc
	v_cndmask_b32_e64 v179, v170, -v174, s[8:9]
	v_cndmask_b32_e32 v186, v175, v171, vcc
	v_cndmask_b32_e64 v187, v174, v170, s[8:9]
	v_cmp_eq_u32_e32 vcc, 1, v169
	v_cmp_eq_u32_e64 s[8:9], 1, v134
	v_pk_fma_f32 v[180:181], v[176:177], s[60:61], v[180:181] op_sel_hi:[1,0,0] neg_lo:[1,0,0] neg_hi:[1,0,0]
	v_cndmask_b32_e64 v179, v179, -v170, vcc
	v_cndmask_b32_e64 v178, v178, -v171, s[8:9]
	v_cndmask_b32_e64 v187, -v187, v174, vcc
	v_cndmask_b32_e64 v186, -v186, v175, s[8:9]
	v_cmp_eq_u32_e32 vcc, 0, v134
	v_cmp_eq_u32_e64 s[8:9], 0, v169
	v_pk_fma_f32 v[180:181], v[176:177], v[180:181], s[64:65] op_sel_hi:[1,1,0]
	v_cndmask_b32_e32 v171, v186, v171, vcc
	v_cndmask_b32_e64 v170, v187, v170, s[8:9]
	v_pk_fma_f32 v[180:181], v[176:177], v[180:181], s[66:67] op_sel_hi:[1,1,0]
	v_cndmask_b32_e32 v175, v178, v175, vcc
	v_cndmask_b32_e64 v174, v179, v174, s[8:9]
	v_pk_mul_f32 v[178:179], v[118:119], v[170:171]
	v_pk_mul_f32 v[186:187], v[114:115], v[170:171]
	v_pk_fma_f32 v[170:171], v[114:115], v[174:175], v[178:179]
	v_pk_fma_f32 v[178:179], v[176:177], v[180:181], -0.5 op_sel_hi:[1,1,0]
	v_cmp_eq_u32_e32 vcc, 2, v190
	v_pk_fma_f32 v[176:177], v[176:177], v[178:179], 1.0 op_sel_hi:[1,1,0]
	v_cmp_eq_u32_e64 s[8:9], 2, v191
	v_cndmask_b32_e64 v134, v173, -v177, vcc
	v_cmp_eq_u32_e64 s[10:11], 1, v191
	v_cndmask_b32_e64 v169, v172, -v176, s[8:9]
	v_cmp_eq_u32_e64 s[12:13], 1, v190
	v_cndmask_b32_e64 v169, v169, -v172, s[10:11]
	v_cmp_eq_u32_e64 s[14:15], 0, v190
	v_cndmask_b32_e64 v134, v134, -v173, s[12:13]
	v_cmp_eq_u32_e64 s[16:17], 0, v191
	v_cndmask_b32_e64 v179, v134, v177, s[14:15]
	v_cndmask_b32_e32 v134, v177, v173, vcc
	v_cndmask_b32_e64 v178, v169, v176, s[16:17]
	v_cndmask_b32_e64 v169, v176, v172, s[8:9]
	v_cndmask_b32_e64 v169, -v169, v176, s[10:11]
	v_cndmask_b32_e64 v134, -v134, v177, s[12:13]
	v_cndmask_b32_e64 v177, v134, v173, s[14:15]
	v_cndmask_b32_e64 v176, v169, v172, s[16:17]
	v_pk_mul_f32 v[172:173], v[120:121], v[176:177]
	v_pk_mul_f32 v[176:177], v[116:117], v[176:177]
	v_lshlrev_b32_e32 v134, 2, v136
	v_pk_fma_f32 v[174:175], v[118:119], v[174:175], v[186:187] neg_lo:[0,0,1] neg_hi:[0,0,1]
	v_pk_fma_f32 v[172:173], v[116:117], v[178:179], v[172:173]
	v_pk_fma_f32 v[176:177], v[120:121], v[178:179], v[176:177] neg_lo:[0,0,1] neg_hi:[0,0,1]
	v_lshl_add_u64 v[178:179], v[182:183], 0, v[134:135]
	v_lshlrev_b32_e32 v134, 1, v136
	global_store_dwordx4 v[178:179], v[174:177], off
	global_store_dwordx4 v[178:179], v[170:173], off offset:64
	s_nop 0
	v_cvt_pk_bf16_f32 v174, v174, v175
	v_cvt_pk_bf16_f32 v175, v176, v177
	s_nop 0
	v_cvt_pk_bf16_f32 v170, v170, v171
	v_cvt_pk_bf16_f32 v171, v172, v173
	v_lshl_add_u64 v[172:173], v[184:185], 0, v[134:135]
	global_store_dwordx2 v[172:173], v[174:175], off offset:256
	global_store_dwordx2 v[172:173], v[170:171], off offset:288

.LBB0_357:
	s_or_b64 exec, exec, s[14:15]
	s_andn2_b64 vcc, exec, s[40:41]
	s_cbranch_vccnz .LBB0_359
	s_waitcnt lgkmcnt(0)
	v_mov_b32_e32 v122, v246
	v_mov_b32_e32 v123, v247
	v_mov_b32_e32 v124, v248
	v_mov_b32_e32 v125, v249
	v_and_b32_e32 v121, 0x1fdf, v114
	v_cmp_gt_i32_e32 vcc, s77, v114
	v_readlane_b32 s14, v255, 0
	v_add_u32_e32 v134, 0xffffc010, v154
	v_cndmask_b32_e32 v121, v158, v121, vcc
	v_readlane_b32 s15, v255, 1
	v_lshlrev_b64 v[168:169], 7, v[134:135]
	v_cndmask_b32_e32 v170, v134, v114, vcc
	s_load_dwordx4 s[0:3], s[14:15], 0x108
	v_cvt_f32_u32_e32 v134, v121
	v_lshlrev_b64 v[126:127], 7, v[114:115]
	v_mov_b32_e32 v129, v135
	v_lshl_add_u64 v[126:127], s[46:47], 0, v[126:127]
	v_cndmask_b32_e32 v128, v164, v165, vcc
	v_lshl_add_u64 v[168:169], s[44:45], 0, v[168:169]
	s_waitcnt lgkmcnt(0)
	v_lshl_add_u64 v[128:129], s[2:3], 0, v[128:129]
	v_cndmask_b32_e32 v169, v169, v127, vcc
	v_cndmask_b32_e32 v168, v168, v126, vcc
	v_mad_u64_u32 v[170:171], s[0:1], v170, s95, v[128:129]
	v_mov_b64_e32 v[156:157], s[54:55]
	v_mov_b64_e32 v[166:167], s[62:63]
	v_cndmask_b32_e32 v155, 0, v115, vcc
	v_mad_i32_i24 v171, v155, s95, v171
	v_pk_mul_f32 v[122:123], v[122:123], v[134:135] op_sel_hi:[1,0]
	v_pk_mul_f32 v[124:125], v[124:125], v[134:135] op_sel_hi:[1,0]
	v_cvt_f64_f32_e32 v[126:127], v122
	v_cvt_f64_f32_e32 v[122:123], v123
	v_cvt_f64_f32_e32 v[128:129], v124
	v_cvt_f64_f32_e32 v[124:125], v125
	v_mul_f64 v[172:173], v[122:123], s[48:49]
	v_mul_f64 v[174:175], v[126:127], s[48:49]
	v_mul_f64 v[176:177], v[124:125], s[48:49]
	v_mul_f64 v[178:179], v[128:129], s[48:49]
	v_rndne_f64_e32 v[174:175], v[174:175]
	v_rndne_f64_e32 v[172:173], v[172:173]
	v_rndne_f64_e32 v[178:179], v[178:179]
	v_rndne_f64_e32 v[176:177], v[176:177]
	v_fma_f64 v[122:123], v[122:123], s[48:49], -v[172:173]
	v_fma_f64 v[126:127], v[126:127], s[48:49], -v[174:175]
	v_fma_f64 v[124:125], v[124:125], s[48:49], -v[176:177]
	v_fma_f64 v[128:129], v[128:129], s[48:49], -v[178:179]
	v_mul_f64 v[126:127], v[126:127], s[50:51]
	v_mul_f64 v[122:123], v[122:123], s[50:51]
	v_mul_f64 v[128:129], v[128:129], s[50:51]
	v_mul_f64 v[124:125], v[124:125], s[50:51]
	v_cvt_f32_f64_e32 v123, v[122:123]
	v_cvt_f32_f64_e32 v122, v[126:127]
	v_cvt_i32_f64_e32 v121, v[172:173]
	v_cvt_i32_f64_e32 v172, v[178:179]
	v_cvt_f32_f64_e32 v125, v[124:125]
	v_cvt_f32_f64_e32 v124, v[128:129]
	v_pk_mul_f32 v[126:127], v[122:123], v[122:123]
	v_cvt_i32_f64_e32 v134, v[174:175]
	v_cvt_i32_f64_e32 v155, v[176:177]
	v_and_b32_e32 v176, 3, v172
	v_pk_mul_f32 v[128:129], v[124:125], v[124:125]
	v_pk_fma_f32 v[172:173], v[126:127], s[52:53], v[156:157] op_sel_hi:[1,0,0]
	v_pk_fma_f32 v[174:175], v[126:127], s[60:61], v[166:167] op_sel_hi:[1,0,0] neg_lo:[1,0,0] neg_hi:[1,0,0]
	v_pk_fma_f32 v[156:157], v[128:129], s[52:53], v[156:157] op_sel_hi:[1,0,0]
	v_pk_fma_f32 v[172:173], v[126:127], v[172:173], s[56:57] op_sel_hi:[1,1,0]
	v_pk_fma_f32 v[174:175], v[126:127], v[174:175], s[64:65] op_sel_hi:[1,1,0]
	v_pk_fma_f32 v[156:157], v[128:129], v[156:157], s[56:57] op_sel_hi:[1,1,0]
	v_pk_fma_f32 v[172:173], v[126:127], v[172:173], s[58:59] op_sel_hi:[1,1,0]
	v_pk_fma_f32 v[174:175], v[126:127], v[174:175], s[66:67] op_sel_hi:[1,1,0]
	v_and_b32_e32 v121, 3, v121
	v_and_b32_e32 v134, 3, v134
	v_pk_fma_f32 v[156:157], v[128:129], v[156:157], s[58:59] op_sel_hi:[1,1,0]
	v_pk_fma_f32 v[172:173], v[126:127], v[172:173], 1.0 op_sel_hi:[1,1,0]
	v_pk_fma_f32 v[174:175], v[126:127], v[174:175], -0.5 op_sel_hi:[1,1,0]
	v_pk_fma_f32 v[156:157], v[128:129], v[156:157], 1.0 op_sel_hi:[1,1,0]
	v_pk_mul_f32 v[122:123], v[172:173], v[122:123]
	v_pk_fma_f32 v[126:127], v[126:127], v[174:175], 1.0 op_sel_hi:[1,1,0]
	v_cmp_eq_u32_e32 vcc, 2, v121
	v_cmp_eq_u32_e64 s[14:15], 2, v134
	v_pk_mul_f32 v[124:125], v[156:157], v[124:125]
	v_cndmask_b32_e64 v156, v123, -v127, vcc
	v_cndmask_b32_e64 v157, v122, -v126, s[14:15]
	v_cndmask_b32_e32 v172, v127, v123, vcc
	v_cndmask_b32_e64 v173, v126, v122, s[14:15]
	v_cmp_eq_u32_e32 vcc, 1, v134
	v_cmp_eq_u32_e64 s[14:15], 1, v121
	v_pk_fma_f32 v[166:167], v[128:129], s[60:61], v[166:167] op_sel_hi:[1,0,0] neg_lo:[1,0,0] neg_hi:[1,0,0]
	v_cndmask_b32_e64 v157, v157, -v122, vcc
	v_cndmask_b32_e64 v156, v156, -v123, s[14:15]
	v_cndmask_b32_e64 v173, -v173, v126, vcc
	v_cndmask_b32_e64 v172, -v172, v127, s[14:15]
	v_cmp_eq_u32_e32 vcc, 0, v121
	v_cmp_eq_u32_e64 s[14:15], 0, v134
	v_pk_fma_f32 v[166:167], v[128:129], v[166:167], s[64:65] op_sel_hi:[1,1,0]
	v_cndmask_b32_e32 v123, v172, v123, vcc
	v_cndmask_b32_e64 v122, v173, v122, s[14:15]
	v_pk_fma_f32 v[166:167], v[128:129], v[166:167], s[66:67] op_sel_hi:[1,1,0]
	v_cndmask_b32_e32 v127, v156, v127, vcc
	v_cndmask_b32_e64 v126, v157, v126, s[14:15]
	v_pk_mul_f32 v[156:157], v[102:103], v[122:123]
	v_and_b32_e32 v155, 3, v155
	v_pk_mul_f32 v[172:173], v[98:99], v[122:123]
	v_pk_fma_f32 v[122:123], v[98:99], v[126:127], v[156:157]
	v_pk_fma_f32 v[156:157], v[128:129], v[166:167], -0.5 op_sel_hi:[1,1,0]
	v_cmp_eq_u32_e32 vcc, 2, v155
	v_pk_fma_f32 v[128:129], v[128:129], v[156:157], 1.0 op_sel_hi:[1,1,0]
	v_cmp_eq_u32_e64 s[14:15], 2, v176
	v_cndmask_b32_e64 v121, v125, -v129, vcc
	v_cmp_eq_u32_e64 s[16:17], 1, v176
	v_cndmask_b32_e64 v134, v124, -v128, s[14:15]
	v_cmp_eq_u32_e64 s[18:19], 1, v155
	v_cndmask_b32_e64 v134, v134, -v124, s[16:17]
	v_cmp_eq_u32_e64 s[20:21], 0, v155
	v_cndmask_b32_e64 v121, v121, -v125, s[18:19]
	v_cmp_eq_u32_e64 s[22:23], 0, v176
	v_cndmask_b32_e64 v157, v121, v129, s[20:21]
	v_cndmask_b32_e32 v121, v129, v125, vcc
	v_cndmask_b32_e64 v156, v134, v128, s[22:23]
	v_cndmask_b32_e64 v134, v128, v124, s[14:15]
	v_cndmask_b32_e64 v128, -v134, v128, s[16:17]
	v_cndmask_b32_e64 v121, -v121, v129, s[18:19]
	v_cndmask_b32_e64 v129, v121, v125, s[20:21]
	v_cndmask_b32_e64 v128, v128, v124, s[22:23]
	v_pk_mul_f32 v[124:125], v[104:105], v[128:129]
	v_pk_mul_f32 v[128:129], v[100:101], v[128:129]
	v_lshlrev_b32_e32 v134, 2, v136
	v_pk_fma_f32 v[126:127], v[102:103], v[126:127], v[172:173] neg_lo:[0,0,1] neg_hi:[0,0,1]
	v_pk_fma_f32 v[124:125], v[100:101], v[156:157], v[124:125]
	v_pk_fma_f32 v[128:129], v[104:105], v[156:157], v[128:129] neg_lo:[0,0,1] neg_hi:[0,0,1]
	v_lshl_add_u64 v[156:157], v[168:169], 0, v[134:135]
	v_lshlrev_b32_e32 v134, 1, v136
	global_store_dwordx4 v[156:157], v[126:129], off
	global_store_dwordx4 v[156:157], v[122:125], off offset:64
	s_nop 0
	v_cvt_pk_bf16_f32 v126, v126, v127
	v_cvt_pk_bf16_f32 v127, v128, v129
	s_nop 0
	v_cvt_pk_bf16_f32 v122, v122, v123
	v_cvt_pk_bf16_f32 v123, v124, v125
	v_lshl_add_u64 v[124:125], v[170:171], 0, v[134:135]
	global_store_dwordx2 v[124:125], v[126:127], off offset:256
	global_store_dwordx2 v[124:125], v[122:123], off offset:288

.LBB0_379:
	s_or_b64 exec, exec, s[14:15]
	s_andn2_b64 vcc, exec, s[40:41]
	s_cbranch_vccnz .LBB0_381
	s_waitcnt lgkmcnt(0)
	v_mov_b32_e32 v106, v246
	v_mov_b32_e32 v107, v247
	v_mov_b32_e32 v108, v248
	v_mov_b32_e32 v109, v249
	v_readlane_b32 s14, v255, 0
	v_and_b32_e32 v105, 0x1fef, v98
	v_cmp_gt_i32_e32 vcc, s77, v98
	v_readlane_b32 s15, v255, 1
	s_load_dwordx4 s[0:3], s[14:15], 0x108
	v_cndmask_b32_e32 v105, v158, v105, vcc
	v_cvt_f32_u32_e32 v120, v105
	v_add_u32_e32 v134, 0xffffc020, v154
	v_lshlrev_b64 v[110:111], 7, v[98:99]
	v_mov_b32_e32 v113, v135
	v_lshlrev_b64 v[118:119], 7, v[134:135]
	v_cndmask_b32_e32 v112, v164, v165, vcc
	v_cndmask_b32_e32 v121, 0, v99, vcc
	v_lshl_add_u64 v[110:111], s[46:47], 0, v[110:111]
	v_cndmask_b32_e32 v122, v134, v98, vcc
	v_lshl_add_u64 v[118:119], s[44:45], 0, v[118:119]
	s_waitcnt lgkmcnt(0)
	v_lshl_add_u64 v[112:113], s[2:3], 0, v[112:113]
	v_cndmask_b32_e32 v119, v119, v111, vcc
	v_cndmask_b32_e32 v118, v118, v110, vcc
	v_mad_u64_u32 v[122:123], s[0:1], v122, s95, v[112:113]
	v_mad_i32_i24 v123, v121, s95, v123
	v_mov_b64_e32 v[114:115], s[54:55]
	v_mov_b64_e32 v[116:117], s[62:63]
	v_lshlrev_b32_e32 v134, 2, v136
	v_pk_mul_f32 v[106:107], v[106:107], v[120:121] op_sel_hi:[1,0]
	v_pk_mul_f32 v[108:109], v[108:109], v[120:121] op_sel_hi:[1,0]
	v_cvt_f64_f32_e32 v[110:111], v106
	v_cvt_f64_f32_e32 v[106:107], v107
	v_cvt_f64_f32_e32 v[112:113], v108
	v_cvt_f64_f32_e32 v[108:109], v109
	v_mul_f64 v[120:121], v[106:107], s[48:49]
	v_mul_f64 v[124:125], v[110:111], s[48:49]
	v_mul_f64 v[126:127], v[108:109], s[48:49]
	v_mul_f64 v[128:129], v[112:113], s[48:49]
	v_rndne_f64_e32 v[124:125], v[124:125]
	v_rndne_f64_e32 v[120:121], v[120:121]
	v_rndne_f64_e32 v[128:129], v[128:129]
	v_rndne_f64_e32 v[126:127], v[126:127]
	v_fma_f64 v[106:107], v[106:107], s[48:49], -v[120:121]
	v_fma_f64 v[110:111], v[110:111], s[48:49], -v[124:125]
	v_fma_f64 v[108:109], v[108:109], s[48:49], -v[126:127]
	v_fma_f64 v[112:113], v[112:113], s[48:49], -v[128:129]
	v_mul_f64 v[110:111], v[110:111], s[50:51]
	v_mul_f64 v[106:107], v[106:107], s[50:51]
	v_mul_f64 v[112:113], v[112:113], s[50:51]
	v_mul_f64 v[108:109], v[108:109], s[50:51]
	v_cvt_f32_f64_e32 v107, v[106:107]
	v_cvt_f32_f64_e32 v106, v[110:111]
	v_cvt_i32_f64_e32 v105, v[120:121]
	v_cvt_i32_f64_e32 v120, v[124:125]
	v_cvt_i32_f64_e32 v121, v[126:127]
	v_cvt_i32_f64_e32 v124, v[128:129]
	v_cvt_f32_f64_e32 v109, v[108:109]
	v_cvt_f32_f64_e32 v108, v[112:113]
	v_pk_mul_f32 v[110:111], v[106:107], v[106:107]
	v_and_b32_e32 v126, 3, v120
	v_and_b32_e32 v127, 3, v121
	v_and_b32_e32 v128, 3, v124
	v_pk_mul_f32 v[112:113], v[108:109], v[108:109]
	v_pk_fma_f32 v[120:121], v[110:111], s[52:53], v[114:115] op_sel_hi:[1,0,0]
	v_pk_fma_f32 v[124:125], v[110:111], s[60:61], v[116:117] op_sel_hi:[1,0,0] neg_lo:[1,0,0] neg_hi:[1,0,0]
	v_pk_fma_f32 v[114:115], v[112:113], s[52:53], v[114:115] op_sel_hi:[1,0,0]
	v_pk_fma_f32 v[120:121], v[110:111], v[120:121], s[56:57] op_sel_hi:[1,1,0]
	v_pk_fma_f32 v[124:125], v[110:111], v[124:125], s[64:65] op_sel_hi:[1,1,0]
	v_pk_fma_f32 v[114:115], v[112:113], v[114:115], s[56:57] op_sel_hi:[1,1,0]
	v_pk_fma_f32 v[120:121], v[110:111], v[120:121], s[58:59] op_sel_hi:[1,1,0]
	v_pk_fma_f32 v[124:125], v[110:111], v[124:125], s[66:67] op_sel_hi:[1,1,0]
	v_and_b32_e32 v105, 3, v105
	v_pk_fma_f32 v[114:115], v[112:113], v[114:115], s[58:59] op_sel_hi:[1,1,0]
	v_pk_fma_f32 v[120:121], v[110:111], v[120:121], 1.0 op_sel_hi:[1,1,0]
	v_pk_fma_f32 v[124:125], v[110:111], v[124:125], -0.5 op_sel_hi:[1,1,0]
	v_pk_fma_f32 v[114:115], v[112:113], v[114:115], 1.0 op_sel_hi:[1,1,0]
	v_pk_mul_f32 v[106:107], v[120:121], v[106:107]
	v_pk_fma_f32 v[110:111], v[110:111], v[124:125], 1.0 op_sel_hi:[1,1,0]
	v_cmp_eq_u32_e32 vcc, 2, v105
	v_cmp_eq_u32_e64 s[14:15], 2, v126
	v_pk_mul_f32 v[108:109], v[114:115], v[108:109]
	v_cndmask_b32_e64 v114, v107, -v111, vcc
	v_cndmask_b32_e64 v115, v106, -v110, s[14:15]
	v_cndmask_b32_e32 v120, v111, v107, vcc
	v_cndmask_b32_e64 v121, v110, v106, s[14:15]
	v_cmp_eq_u32_e32 vcc, 1, v126
	v_cmp_eq_u32_e64 s[14:15], 1, v105
	v_pk_fma_f32 v[116:117], v[112:113], s[60:61], v[116:117] op_sel_hi:[1,0,0] neg_lo:[1,0,0] neg_hi:[1,0,0]
	v_cndmask_b32_e64 v115, v115, -v106, vcc
	v_cndmask_b32_e64 v114, v114, -v107, s[14:15]
	v_cndmask_b32_e64 v121, -v121, v110, vcc
	v_cndmask_b32_e64 v120, -v120, v111, s[14:15]
	v_cmp_eq_u32_e32 vcc, 0, v105
	v_cmp_eq_u32_e64 s[14:15], 0, v126
	v_pk_fma_f32 v[116:117], v[112:113], v[116:117], s[64:65] op_sel_hi:[1,1,0]
	v_cndmask_b32_e32 v107, v120, v107, vcc
	v_cndmask_b32_e64 v106, v121, v106, s[14:15]
	v_pk_fma_f32 v[116:117], v[112:113], v[116:117], s[66:67] op_sel_hi:[1,1,0]
	v_cndmask_b32_e32 v111, v114, v111, vcc
	v_cndmask_b32_e64 v110, v115, v110, s[14:15]
	v_pk_mul_f32 v[114:115], v[86:87], v[106:107]
	v_pk_mul_f32 v[120:121], v[82:83], v[106:107]
	v_pk_fma_f32 v[106:107], v[82:83], v[110:111], v[114:115]
	v_pk_fma_f32 v[114:115], v[112:113], v[116:117], -0.5 op_sel_hi:[1,1,0]
	v_cmp_eq_u32_e32 vcc, 2, v127
	v_pk_fma_f32 v[112:113], v[112:113], v[114:115], 1.0 op_sel_hi:[1,1,0]
	v_cmp_eq_u32_e64 s[14:15], 2, v128
	v_cndmask_b32_e64 v105, v109, -v113, vcc
	v_cmp_eq_u32_e64 s[18:19], 1, v127
	v_cndmask_b32_e64 v114, v108, -v112, s[14:15]
	v_cmp_eq_u32_e64 s[16:17], 1, v128
	v_cndmask_b32_e64 v105, v105, -v109, s[18:19]
	v_cmp_eq_u32_e64 s[20:21], 0, v127
	v_cndmask_b32_e64 v114, v114, -v108, s[16:17]
	v_cmp_eq_u32_e64 s[22:23], 0, v128
	v_cndmask_b32_e64 v115, v105, v113, s[20:21]
	v_cndmask_b32_e32 v105, v113, v109, vcc
	v_cndmask_b32_e64 v116, v112, v108, s[14:15]
	v_cndmask_b32_e64 v114, v114, v112, s[22:23]
	v_cndmask_b32_e64 v112, -v116, v112, s[16:17]
	v_cndmask_b32_e64 v105, -v105, v113, s[18:19]
	v_cndmask_b32_e64 v113, v105, v109, s[20:21]
	v_cndmask_b32_e64 v112, v112, v108, s[22:23]
	v_pk_mul_f32 v[108:109], v[88:89], v[112:113]
	v_pk_mul_f32 v[112:113], v[84:85], v[112:113]
	v_pk_fma_f32 v[110:111], v[86:87], v[110:111], v[120:121] neg_lo:[0,0,1] neg_hi:[0,0,1]
	v_pk_fma_f32 v[108:109], v[84:85], v[114:115], v[108:109]
	v_pk_fma_f32 v[112:113], v[88:89], v[114:115], v[112:113] neg_lo:[0,0,1] neg_hi:[0,0,1]
	v_lshl_add_u64 v[114:115], v[118:119], 0, v[134:135]
	v_lshlrev_b32_e32 v134, 1, v136
	global_store_dwordx4 v[114:115], v[110:113], off
	global_store_dwordx4 v[114:115], v[106:109], off offset:64
	s_nop 0
	v_cvt_pk_bf16_f32 v110, v110, v111
	v_cvt_pk_bf16_f32 v111, v112, v113
	s_nop 0
	v_cvt_pk_bf16_f32 v106, v106, v107
	v_cvt_pk_bf16_f32 v107, v108, v109
	v_lshl_add_u64 v[108:109], v[122:123], 0, v[134:135]
	global_store_dwordx2 v[108:109], v[110:111], off offset:256
	global_store_dwordx2 v[108:109], v[106:107], off offset:288

.LBB0_401:
	s_or_b64 exec, exec, s[14:15]
	s_andn2_b64 vcc, exec, s[40:41]
	s_cbranch_vccnz .LBB0_403
	s_waitcnt lgkmcnt(0)
	v_mov_b32_e32 v90, v246
	v_mov_b32_e32 v91, v247
	v_mov_b32_e32 v92, v248
	v_mov_b32_e32 v93, v249
	v_readlane_b32 s14, v255, 0
	v_and_b32_e32 v89, 0x1fff, v82
	v_cmp_gt_i32_e32 vcc, s77, v82
	v_readlane_b32 s15, v255, 1
	s_load_dwordx4 s[0:3], s[14:15], 0x108
	v_cndmask_b32_e32 v89, v158, v89, vcc
	v_cvt_f32_u32_e32 v104, v89
	v_add_u32_e32 v134, 0xffffc030, v154
	v_lshlrev_b64 v[94:95], 7, v[82:83]
	v_mov_b32_e32 v97, v135
	v_lshlrev_b64 v[102:103], 7, v[134:135]
	v_cndmask_b32_e32 v96, v164, v165, vcc
	v_cndmask_b32_e32 v105, 0, v83, vcc
	v_lshl_add_u64 v[94:95], s[46:47], 0, v[94:95]
	v_cndmask_b32_e32 v106, v134, v82, vcc
	v_lshl_add_u64 v[102:103], s[44:45], 0, v[102:103]
	s_waitcnt lgkmcnt(0)
	v_lshl_add_u64 v[96:97], s[2:3], 0, v[96:97]
	v_cndmask_b32_e32 v103, v103, v95, vcc
	v_cndmask_b32_e32 v102, v102, v94, vcc
	v_mad_u64_u32 v[106:107], s[0:1], v106, s95, v[96:97]
	v_mad_i32_i24 v107, v105, s95, v107
	v_mov_b64_e32 v[98:99], s[54:55]
	v_mov_b64_e32 v[100:101], s[62:63]
	v_lshlrev_b32_e32 v134, 2, v136
	v_pk_mul_f32 v[90:91], v[90:91], v[104:105] op_sel_hi:[1,0]
	v_pk_mul_f32 v[92:93], v[92:93], v[104:105] op_sel_hi:[1,0]
	v_cvt_f64_f32_e32 v[94:95], v90
	v_cvt_f64_f32_e32 v[90:91], v91
	v_cvt_f64_f32_e32 v[96:97], v92
	v_cvt_f64_f32_e32 v[92:93], v93
	v_mul_f64 v[104:105], v[90:91], s[48:49]
	v_mul_f64 v[108:109], v[94:95], s[48:49]
	v_mul_f64 v[110:111], v[92:93], s[48:49]
	v_mul_f64 v[112:113], v[96:97], s[48:49]
	v_rndne_f64_e32 v[108:109], v[108:109]
	v_rndne_f64_e32 v[104:105], v[104:105]
	v_rndne_f64_e32 v[112:113], v[112:113]
	v_rndne_f64_e32 v[110:111], v[110:111]
	v_fma_f64 v[90:91], v[90:91], s[48:49], -v[104:105]
	v_fma_f64 v[94:95], v[94:95], s[48:49], -v[108:109]
	v_fma_f64 v[92:93], v[92:93], s[48:49], -v[110:111]
	v_fma_f64 v[96:97], v[96:97], s[48:49], -v[112:113]
	v_mul_f64 v[94:95], v[94:95], s[50:51]
	v_mul_f64 v[90:91], v[90:91], s[50:51]
	v_mul_f64 v[96:97], v[96:97], s[50:51]
	v_mul_f64 v[92:93], v[92:93], s[50:51]
	v_cvt_f32_f64_e32 v91, v[90:91]
	v_cvt_f32_f64_e32 v90, v[94:95]
	v_cvt_i32_f64_e32 v89, v[104:105]
	v_cvt_i32_f64_e32 v104, v[108:109]
	v_cvt_i32_f64_e32 v105, v[110:111]
	v_cvt_i32_f64_e32 v108, v[112:113]
	v_cvt_f32_f64_e32 v93, v[92:93]
	v_cvt_f32_f64_e32 v92, v[96:97]
	v_pk_mul_f32 v[94:95], v[90:91], v[90:91]
	v_and_b32_e32 v110, 3, v104
	v_and_b32_e32 v111, 3, v105
	v_and_b32_e32 v112, 3, v108
	v_pk_mul_f32 v[96:97], v[92:93], v[92:93]
	v_pk_fma_f32 v[104:105], v[94:95], s[52:53], v[98:99] op_sel_hi:[1,0,0]
	v_pk_fma_f32 v[108:109], v[94:95], s[60:61], v[100:101] op_sel_hi:[1,0,0] neg_lo:[1,0,0] neg_hi:[1,0,0]
	v_pk_fma_f32 v[98:99], v[96:97], s[52:53], v[98:99] op_sel_hi:[1,0,0]
	v_pk_fma_f32 v[104:105], v[94:95], v[104:105], s[56:57] op_sel_hi:[1,1,0]
	v_pk_fma_f32 v[108:109], v[94:95], v[108:109], s[64:65] op_sel_hi:[1,1,0]
	v_pk_fma_f32 v[98:99], v[96:97], v[98:99], s[56:57] op_sel_hi:[1,1,0]
	v_pk_fma_f32 v[104:105], v[94:95], v[104:105], s[58:59] op_sel_hi:[1,1,0]
	v_pk_fma_f32 v[108:109], v[94:95], v[108:109], s[66:67] op_sel_hi:[1,1,0]
	v_and_b32_e32 v89, 3, v89
	v_pk_fma_f32 v[98:99], v[96:97], v[98:99], s[58:59] op_sel_hi:[1,1,0]
	v_pk_fma_f32 v[104:105], v[94:95], v[104:105], 1.0 op_sel_hi:[1,1,0]
	v_pk_fma_f32 v[108:109], v[94:95], v[108:109], -0.5 op_sel_hi:[1,1,0]
	v_pk_fma_f32 v[98:99], v[96:97], v[98:99], 1.0 op_sel_hi:[1,1,0]
	v_pk_mul_f32 v[90:91], v[104:105], v[90:91]
	v_pk_fma_f32 v[94:95], v[94:95], v[108:109], 1.0 op_sel_hi:[1,1,0]
	v_cmp_eq_u32_e32 vcc, 2, v89
	v_cmp_eq_u32_e64 s[14:15], 2, v110
	v_pk_mul_f32 v[92:93], v[98:99], v[92:93]
	v_cndmask_b32_e64 v98, v91, -v95, vcc
	v_cndmask_b32_e64 v99, v90, -v94, s[14:15]
	v_cndmask_b32_e32 v104, v95, v91, vcc
	v_cndmask_b32_e64 v105, v94, v90, s[14:15]
	v_cmp_eq_u32_e32 vcc, 1, v110
	v_cmp_eq_u32_e64 s[14:15], 1, v89
	v_pk_fma_f32 v[100:101], v[96:97], s[60:61], v[100:101] op_sel_hi:[1,0,0] neg_lo:[1,0,0] neg_hi:[1,0,0]
	v_cndmask_b32_e64 v99, v99, -v90, vcc
	v_cndmask_b32_e64 v98, v98, -v91, s[14:15]
	v_cndmask_b32_e64 v105, -v105, v94, vcc
	v_cndmask_b32_e64 v104, -v104, v95, s[14:15]
	v_cmp_eq_u32_e32 vcc, 0, v89
	v_cmp_eq_u32_e64 s[14:15], 0, v110
	v_pk_fma_f32 v[100:101], v[96:97], v[100:101], s[64:65] op_sel_hi:[1,1,0]
	v_cndmask_b32_e32 v91, v104, v91, vcc
	v_cndmask_b32_e64 v90, v105, v90, s[14:15]
	v_pk_fma_f32 v[100:101], v[96:97], v[100:101], s[66:67] op_sel_hi:[1,1,0]
	v_cndmask_b32_e32 v95, v98, v95, vcc
	v_cndmask_b32_e64 v94, v99, v94, s[14:15]
	v_pk_mul_f32 v[98:99], v[70:71], v[90:91]
	v_pk_mul_f32 v[104:105], v[66:67], v[90:91]
	v_pk_fma_f32 v[90:91], v[66:67], v[94:95], v[98:99]
	v_pk_fma_f32 v[98:99], v[96:97], v[100:101], -0.5 op_sel_hi:[1,1,0]
	v_cmp_eq_u32_e32 vcc, 2, v111
	v_pk_fma_f32 v[96:97], v[96:97], v[98:99], 1.0 op_sel_hi:[1,1,0]
	v_cmp_eq_u32_e64 s[14:15], 2, v112
	v_cndmask_b32_e64 v89, v93, -v97, vcc
	v_cmp_eq_u32_e64 s[18:19], 1, v111
	v_cndmask_b32_e64 v98, v92, -v96, s[14:15]
	v_cmp_eq_u32_e64 s[16:17], 1, v112
	v_cndmask_b32_e64 v89, v89, -v93, s[18:19]
	v_cmp_eq_u32_e64 s[20:21], 0, v111
	v_cndmask_b32_e64 v98, v98, -v92, s[16:17]
	v_cmp_eq_u32_e64 s[22:23], 0, v112
	v_cndmask_b32_e64 v99, v89, v97, s[20:21]
	v_cndmask_b32_e32 v89, v97, v93, vcc
	v_cndmask_b32_e64 v100, v96, v92, s[14:15]
	v_cndmask_b32_e64 v98, v98, v96, s[22:23]
	v_cndmask_b32_e64 v96, -v100, v96, s[16:17]
	v_cndmask_b32_e64 v89, -v89, v97, s[18:19]
	v_cndmask_b32_e64 v97, v89, v93, s[20:21]
	v_cndmask_b32_e64 v96, v96, v92, s[22:23]
	v_pk_mul_f32 v[92:93], v[72:73], v[96:97]
	v_pk_mul_f32 v[96:97], v[68:69], v[96:97]
	v_pk_fma_f32 v[94:95], v[70:71], v[94:95], v[104:105] neg_lo:[0,0,1] neg_hi:[0,0,1]
	v_pk_fma_f32 v[92:93], v[68:69], v[98:99], v[92:93]
	v_pk_fma_f32 v[96:97], v[72:73], v[98:99], v[96:97] neg_lo:[0,0,1] neg_hi:[0,0,1]
	v_lshl_add_u64 v[98:99], v[102:103], 0, v[134:135]
	v_lshlrev_b32_e32 v134, 1, v136
	global_store_dwordx4 v[98:99], v[94:97], off
	global_store_dwordx4 v[98:99], v[90:93], off offset:64
	s_nop 0
	v_cvt_pk_bf16_f32 v94, v94, v95
	v_cvt_pk_bf16_f32 v95, v96, v97
	s_nop 0
	v_cvt_pk_bf16_f32 v90, v90, v91
	v_cvt_pk_bf16_f32 v91, v92, v93
	v_lshl_add_u64 v[92:93], v[106:107], 0, v[134:135]
	global_store_dwordx2 v[92:93], v[94:95], off offset:256
	global_store_dwordx2 v[92:93], v[90:91], off offset:288

.LBB0_423:
	s_or_b64 exec, exec, s[14:15]
	s_andn2_b64 vcc, exec, s[40:41]
	s_cbranch_vccnz .LBB0_425
	s_waitcnt lgkmcnt(0)
	v_mov_b32_e32 v74, v246
	v_mov_b32_e32 v75, v247
	v_mov_b32_e32 v76, v248
	v_mov_b32_e32 v77, v249
	v_readlane_b32 s14, v255, 0
	v_and_b32_e32 v73, 0x1fcf, v66
	v_cmp_gt_i32_e32 vcc, s77, v66
	v_readlane_b32 s15, v255, 1
	s_load_dwordx4 s[0:3], s[14:15], 0x108
	v_cndmask_b32_e32 v73, v158, v73, vcc
	v_cvt_f32_u32_e32 v88, v73
	v_add_u32_e32 v134, 0xffffc080, v154
	v_lshlrev_b64 v[78:79], 7, v[66:67]
	v_mov_b32_e32 v81, v135
	v_lshlrev_b64 v[86:87], 7, v[134:135]
	v_cndmask_b32_e32 v80, v164, v165, vcc
	v_cndmask_b32_e32 v89, 0, v67, vcc
	v_lshl_add_u64 v[78:79], s[46:47], 0, v[78:79]
	v_cndmask_b32_e32 v90, v134, v66, vcc
	v_lshl_add_u64 v[86:87], s[44:45], 0, v[86:87]
	s_waitcnt lgkmcnt(0)
	v_lshl_add_u64 v[80:81], s[2:3], 0, v[80:81]
	v_cndmask_b32_e32 v87, v87, v79, vcc
	v_cndmask_b32_e32 v86, v86, v78, vcc
	v_mad_u64_u32 v[90:91], s[0:1], v90, s95, v[80:81]
	v_mad_i32_i24 v91, v89, s95, v91
	v_mov_b64_e32 v[82:83], s[54:55]
	v_mov_b64_e32 v[84:85], s[62:63]
	v_lshlrev_b32_e32 v134, 2, v136
	v_pk_mul_f32 v[74:75], v[74:75], v[88:89] op_sel_hi:[1,0]
	v_pk_mul_f32 v[76:77], v[76:77], v[88:89] op_sel_hi:[1,0]
	v_cvt_f64_f32_e32 v[78:79], v74
	v_cvt_f64_f32_e32 v[74:75], v75
	v_cvt_f64_f32_e32 v[80:81], v76
	v_cvt_f64_f32_e32 v[76:77], v77
	v_mul_f64 v[88:89], v[74:75], s[48:49]
	v_mul_f64 v[92:93], v[78:79], s[48:49]
	v_mul_f64 v[94:95], v[76:77], s[48:49]
	v_mul_f64 v[96:97], v[80:81], s[48:49]
	v_rndne_f64_e32 v[92:93], v[92:93]
	v_rndne_f64_e32 v[88:89], v[88:89]
	v_rndne_f64_e32 v[96:97], v[96:97]
	v_rndne_f64_e32 v[94:95], v[94:95]
	v_fma_f64 v[74:75], v[74:75], s[48:49], -v[88:89]
	v_fma_f64 v[78:79], v[78:79], s[48:49], -v[92:93]
	v_fma_f64 v[76:77], v[76:77], s[48:49], -v[94:95]
	v_fma_f64 v[80:81], v[80:81], s[48:49], -v[96:97]
	v_mul_f64 v[78:79], v[78:79], s[50:51]
	v_mul_f64 v[74:75], v[74:75], s[50:51]
	v_mul_f64 v[80:81], v[80:81], s[50:51]
	v_mul_f64 v[76:77], v[76:77], s[50:51]
	v_cvt_f32_f64_e32 v75, v[74:75]
	v_cvt_f32_f64_e32 v74, v[78:79]
	v_cvt_i32_f64_e32 v73, v[88:89]
	v_cvt_i32_f64_e32 v88, v[92:93]
	v_cvt_i32_f64_e32 v89, v[94:95]
	v_cvt_i32_f64_e32 v92, v[96:97]
	v_cvt_f32_f64_e32 v77, v[76:77]
	v_cvt_f32_f64_e32 v76, v[80:81]
	v_pk_mul_f32 v[78:79], v[74:75], v[74:75]
	v_and_b32_e32 v94, 3, v88
	v_and_b32_e32 v95, 3, v89
	v_and_b32_e32 v96, 3, v92
	v_pk_mul_f32 v[80:81], v[76:77], v[76:77]
	v_pk_fma_f32 v[88:89], v[78:79], s[52:53], v[82:83] op_sel_hi:[1,0,0]
	v_pk_fma_f32 v[92:93], v[78:79], s[60:61], v[84:85] op_sel_hi:[1,0,0] neg_lo:[1,0,0] neg_hi:[1,0,0]
	v_pk_fma_f32 v[82:83], v[80:81], s[52:53], v[82:83] op_sel_hi:[1,0,0]
	v_pk_fma_f32 v[88:89], v[78:79], v[88:89], s[56:57] op_sel_hi:[1,1,0]
	v_pk_fma_f32 v[92:93], v[78:79], v[92:93], s[64:65] op_sel_hi:[1,1,0]
	v_pk_fma_f32 v[82:83], v[80:81], v[82:83], s[56:57] op_sel_hi:[1,1,0]
	v_pk_fma_f32 v[88:89], v[78:79], v[88:89], s[58:59] op_sel_hi:[1,1,0]
	v_pk_fma_f32 v[92:93], v[78:79], v[92:93], s[66:67] op_sel_hi:[1,1,0]
	v_and_b32_e32 v73, 3, v73
	v_pk_fma_f32 v[82:83], v[80:81], v[82:83], s[58:59] op_sel_hi:[1,1,0]
	v_pk_fma_f32 v[88:89], v[78:79], v[88:89], 1.0 op_sel_hi:[1,1,0]
	v_pk_fma_f32 v[92:93], v[78:79], v[92:93], -0.5 op_sel_hi:[1,1,0]
	v_pk_fma_f32 v[82:83], v[80:81], v[82:83], 1.0 op_sel_hi:[1,1,0]
	v_pk_mul_f32 v[74:75], v[88:89], v[74:75]
	v_pk_fma_f32 v[78:79], v[78:79], v[92:93], 1.0 op_sel_hi:[1,1,0]
	v_cmp_eq_u32_e32 vcc, 2, v73
	v_cmp_eq_u32_e64 s[14:15], 2, v94
	v_pk_mul_f32 v[76:77], v[82:83], v[76:77]
	v_cndmask_b32_e64 v82, v75, -v79, vcc
	v_cndmask_b32_e64 v83, v74, -v78, s[14:15]
	v_cndmask_b32_e32 v88, v79, v75, vcc
	v_cndmask_b32_e64 v89, v78, v74, s[14:15]
	v_cmp_eq_u32_e32 vcc, 1, v94
	v_cmp_eq_u32_e64 s[14:15], 1, v73
	v_pk_fma_f32 v[84:85], v[80:81], s[60:61], v[84:85] op_sel_hi:[1,0,0] neg_lo:[1,0,0] neg_hi:[1,0,0]
	v_cndmask_b32_e64 v83, v83, -v74, vcc
	v_cndmask_b32_e64 v82, v82, -v75, s[14:15]
	v_cndmask_b32_e64 v89, -v89, v78, vcc
	v_cndmask_b32_e64 v88, -v88, v79, s[14:15]
	v_cmp_eq_u32_e32 vcc, 0, v73
	v_cmp_eq_u32_e64 s[14:15], 0, v94
	v_pk_fma_f32 v[84:85], v[80:81], v[84:85], s[64:65] op_sel_hi:[1,1,0]
	v_cndmask_b32_e32 v75, v88, v75, vcc
	v_cndmask_b32_e64 v74, v89, v74, s[14:15]
	v_pk_fma_f32 v[84:85], v[80:81], v[84:85], s[66:67] op_sel_hi:[1,1,0]
	v_cndmask_b32_e32 v79, v82, v79, vcc
	v_cndmask_b32_e64 v78, v83, v78, s[14:15]
	v_pk_mul_f32 v[82:83], v[54:55], v[74:75]
	v_pk_mul_f32 v[88:89], v[50:51], v[74:75]
	v_pk_fma_f32 v[74:75], v[50:51], v[78:79], v[82:83]
	v_pk_fma_f32 v[82:83], v[80:81], v[84:85], -0.5 op_sel_hi:[1,1,0]
	v_cmp_eq_u32_e32 vcc, 2, v95
	v_pk_fma_f32 v[80:81], v[80:81], v[82:83], 1.0 op_sel_hi:[1,1,0]
	v_cmp_eq_u32_e64 s[14:15], 2, v96
	v_cndmask_b32_e64 v73, v77, -v81, vcc
	v_cmp_eq_u32_e64 s[18:19], 1, v95
	v_cndmask_b32_e64 v82, v76, -v80, s[14:15]
	v_cmp_eq_u32_e64 s[16:17], 1, v96
	v_cndmask_b32_e64 v73, v73, -v77, s[18:19]
	v_cmp_eq_u32_e64 s[20:21], 0, v95
	v_cndmask_b32_e64 v82, v82, -v76, s[16:17]
	v_cmp_eq_u32_e64 s[22:23], 0, v96
	v_cndmask_b32_e64 v83, v73, v81, s[20:21]
	v_cndmask_b32_e32 v73, v81, v77, vcc
	v_cndmask_b32_e64 v84, v80, v76, s[14:15]
	v_cndmask_b32_e64 v82, v82, v80, s[22:23]
	v_cndmask_b32_e64 v80, -v84, v80, s[16:17]
	v_cndmask_b32_e64 v73, -v73, v81, s[18:19]
	v_cndmask_b32_e64 v81, v73, v77, s[20:21]
	v_cndmask_b32_e64 v80, v80, v76, s[22:23]
	v_pk_mul_f32 v[76:77], v[56:57], v[80:81]
	v_pk_mul_f32 v[80:81], v[52:53], v[80:81]
	v_pk_fma_f32 v[78:79], v[54:55], v[78:79], v[88:89] neg_lo:[0,0,1] neg_hi:[0,0,1]
	v_pk_fma_f32 v[76:77], v[52:53], v[82:83], v[76:77]
	v_pk_fma_f32 v[80:81], v[56:57], v[82:83], v[80:81] neg_lo:[0,0,1] neg_hi:[0,0,1]
	v_lshl_add_u64 v[82:83], v[86:87], 0, v[134:135]
	v_lshlrev_b32_e32 v134, 1, v136
	global_store_dwordx4 v[82:83], v[78:81], off
	global_store_dwordx4 v[82:83], v[74:77], off offset:64
	s_nop 0
	v_cvt_pk_bf16_f32 v78, v78, v79
	v_cvt_pk_bf16_f32 v79, v80, v81
	s_nop 0
	v_cvt_pk_bf16_f32 v74, v74, v75
	v_cvt_pk_bf16_f32 v75, v76, v77
	v_lshl_add_u64 v[76:77], v[90:91], 0, v[134:135]
	global_store_dwordx2 v[76:77], v[78:79], off offset:256
	global_store_dwordx2 v[76:77], v[74:75], off offset:288

.LBB0_445:
	s_or_b64 exec, exec, s[14:15]
	s_andn2_b64 vcc, exec, s[40:41]
	s_cbranch_vccnz .LBB0_447
	s_waitcnt lgkmcnt(0)
	v_mov_b32_e32 v58, v246
	v_mov_b32_e32 v59, v247
	v_mov_b32_e32 v60, v248
	v_mov_b32_e32 v61, v249
	v_readlane_b32 s14, v255, 0
	v_and_b32_e32 v57, 0x1fdf, v50
	v_cmp_gt_i32_e32 vcc, s77, v50
	v_readlane_b32 s15, v255, 1
	s_load_dwordx4 s[0:3], s[14:15], 0x108
	v_cndmask_b32_e32 v57, v158, v57, vcc
	v_cvt_f32_u32_e32 v72, v57
	v_add_u32_e32 v134, 0xffffc090, v154
	v_lshlrev_b64 v[62:63], 7, v[50:51]
	v_mov_b32_e32 v65, v135
	v_lshlrev_b64 v[70:71], 7, v[134:135]
	v_cndmask_b32_e32 v64, v164, v165, vcc
	v_cndmask_b32_e32 v73, 0, v51, vcc
	v_lshl_add_u64 v[62:63], s[46:47], 0, v[62:63]
	v_cndmask_b32_e32 v74, v134, v50, vcc
	v_lshl_add_u64 v[70:71], s[44:45], 0, v[70:71]
	s_waitcnt lgkmcnt(0)
	v_lshl_add_u64 v[64:65], s[2:3], 0, v[64:65]
	v_cndmask_b32_e32 v71, v71, v63, vcc
	v_cndmask_b32_e32 v70, v70, v62, vcc
	v_mad_u64_u32 v[74:75], s[0:1], v74, s95, v[64:65]
	v_mad_i32_i24 v75, v73, s95, v75
	v_mov_b64_e32 v[66:67], s[54:55]
	v_mov_b64_e32 v[68:69], s[62:63]
	v_lshlrev_b32_e32 v134, 2, v136
	v_pk_mul_f32 v[58:59], v[58:59], v[72:73] op_sel_hi:[1,0]
	v_pk_mul_f32 v[60:61], v[60:61], v[72:73] op_sel_hi:[1,0]
	v_cvt_f64_f32_e32 v[62:63], v58
	v_cvt_f64_f32_e32 v[58:59], v59
	v_cvt_f64_f32_e32 v[64:65], v60
	v_cvt_f64_f32_e32 v[60:61], v61
	v_mul_f64 v[72:73], v[58:59], s[48:49]
	v_mul_f64 v[76:77], v[62:63], s[48:49]
	v_mul_f64 v[78:79], v[60:61], s[48:49]
	v_mul_f64 v[80:81], v[64:65], s[48:49]
	v_rndne_f64_e32 v[76:77], v[76:77]
	v_rndne_f64_e32 v[72:73], v[72:73]
	v_rndne_f64_e32 v[80:81], v[80:81]
	v_rndne_f64_e32 v[78:79], v[78:79]
	v_fma_f64 v[58:59], v[58:59], s[48:49], -v[72:73]
	v_fma_f64 v[62:63], v[62:63], s[48:49], -v[76:77]
	v_fma_f64 v[60:61], v[60:61], s[48:49], -v[78:79]
	v_fma_f64 v[64:65], v[64:65], s[48:49], -v[80:81]
	v_mul_f64 v[62:63], v[62:63], s[50:51]
	v_mul_f64 v[58:59], v[58:59], s[50:51]
	v_mul_f64 v[64:65], v[64:65], s[50:51]
	v_mul_f64 v[60:61], v[60:61], s[50:51]
	v_cvt_f32_f64_e32 v59, v[58:59]
	v_cvt_f32_f64_e32 v58, v[62:63]
	v_cvt_i32_f64_e32 v57, v[72:73]
	v_cvt_i32_f64_e32 v72, v[76:77]
	v_cvt_i32_f64_e32 v73, v[78:79]
	v_cvt_i32_f64_e32 v76, v[80:81]
	v_cvt_f32_f64_e32 v61, v[60:61]
	v_cvt_f32_f64_e32 v60, v[64:65]
	v_pk_mul_f32 v[62:63], v[58:59], v[58:59]
	v_and_b32_e32 v78, 3, v72
	v_and_b32_e32 v79, 3, v73
	v_and_b32_e32 v80, 3, v76
	v_pk_mul_f32 v[64:65], v[60:61], v[60:61]
	v_pk_fma_f32 v[72:73], v[62:63], s[52:53], v[66:67] op_sel_hi:[1,0,0]
	v_pk_fma_f32 v[76:77], v[62:63], s[60:61], v[68:69] op_sel_hi:[1,0,0] neg_lo:[1,0,0] neg_hi:[1,0,0]
	v_pk_fma_f32 v[66:67], v[64:65], s[52:53], v[66:67] op_sel_hi:[1,0,0]
	v_pk_fma_f32 v[72:73], v[62:63], v[72:73], s[56:57] op_sel_hi:[1,1,0]
	v_pk_fma_f32 v[76:77], v[62:63], v[76:77], s[64:65] op_sel_hi:[1,1,0]
	v_pk_fma_f32 v[66:67], v[64:65], v[66:67], s[56:57] op_sel_hi:[1,1,0]
	v_pk_fma_f32 v[72:73], v[62:63], v[72:73], s[58:59] op_sel_hi:[1,1,0]
	v_pk_fma_f32 v[76:77], v[62:63], v[76:77], s[66:67] op_sel_hi:[1,1,0]
	v_and_b32_e32 v57, 3, v57
	v_pk_fma_f32 v[66:67], v[64:65], v[66:67], s[58:59] op_sel_hi:[1,1,0]
	v_pk_fma_f32 v[72:73], v[62:63], v[72:73], 1.0 op_sel_hi:[1,1,0]
	v_pk_fma_f32 v[76:77], v[62:63], v[76:77], -0.5 op_sel_hi:[1,1,0]
	v_pk_fma_f32 v[66:67], v[64:65], v[66:67], 1.0 op_sel_hi:[1,1,0]
	v_pk_mul_f32 v[58:59], v[72:73], v[58:59]
	v_pk_fma_f32 v[62:63], v[62:63], v[76:77], 1.0 op_sel_hi:[1,1,0]
	v_cmp_eq_u32_e32 vcc, 2, v57
	v_cmp_eq_u32_e64 s[14:15], 2, v78
	v_pk_mul_f32 v[60:61], v[66:67], v[60:61]
	v_cndmask_b32_e64 v66, v59, -v63, vcc
	v_cndmask_b32_e64 v67, v58, -v62, s[14:15]
	v_cndmask_b32_e32 v72, v63, v59, vcc
	v_cndmask_b32_e64 v73, v62, v58, s[14:15]
	v_cmp_eq_u32_e32 vcc, 1, v78
	v_cmp_eq_u32_e64 s[14:15], 1, v57
	v_pk_fma_f32 v[68:69], v[64:65], s[60:61], v[68:69] op_sel_hi:[1,0,0] neg_lo:[1,0,0] neg_hi:[1,0,0]
	v_cndmask_b32_e64 v67, v67, -v58, vcc
	v_cndmask_b32_e64 v66, v66, -v59, s[14:15]
	v_cndmask_b32_e64 v73, -v73, v62, vcc
	v_cndmask_b32_e64 v72, -v72, v63, s[14:15]
	v_cmp_eq_u32_e32 vcc, 0, v57
	v_cmp_eq_u32_e64 s[14:15], 0, v78
	v_pk_fma_f32 v[68:69], v[64:65], v[68:69], s[64:65] op_sel_hi:[1,1,0]
	v_cndmask_b32_e32 v59, v72, v59, vcc
	v_cndmask_b32_e64 v58, v73, v58, s[14:15]
	v_pk_fma_f32 v[68:69], v[64:65], v[68:69], s[66:67] op_sel_hi:[1,1,0]
	v_cndmask_b32_e32 v63, v66, v63, vcc
	v_cndmask_b32_e64 v62, v67, v62, s[14:15]
	v_pk_mul_f32 v[66:67], v[38:39], v[58:59]
	v_pk_mul_f32 v[72:73], v[34:35], v[58:59]
	v_pk_fma_f32 v[58:59], v[34:35], v[62:63], v[66:67]
	v_pk_fma_f32 v[66:67], v[64:65], v[68:69], -0.5 op_sel_hi:[1,1,0]
	v_cmp_eq_u32_e32 vcc, 2, v79
	v_pk_fma_f32 v[64:65], v[64:65], v[66:67], 1.0 op_sel_hi:[1,1,0]
	v_cmp_eq_u32_e64 s[14:15], 2, v80
	v_cndmask_b32_e64 v57, v61, -v65, vcc
	v_cmp_eq_u32_e64 s[18:19], 1, v79
	v_cndmask_b32_e64 v66, v60, -v64, s[14:15]
	v_cmp_eq_u32_e64 s[16:17], 1, v80
	v_cndmask_b32_e64 v57, v57, -v61, s[18:19]
	v_cmp_eq_u32_e64 s[20:21], 0, v79
	v_cndmask_b32_e64 v66, v66, -v60, s[16:17]
	v_cmp_eq_u32_e64 s[22:23], 0, v80
	v_cndmask_b32_e64 v67, v57, v65, s[20:21]
	v_cndmask_b32_e32 v57, v65, v61, vcc
	v_cndmask_b32_e64 v68, v64, v60, s[14:15]
	v_cndmask_b32_e64 v66, v66, v64, s[22:23]
	v_cndmask_b32_e64 v64, -v68, v64, s[16:17]
	v_cndmask_b32_e64 v57, -v57, v65, s[18:19]
	v_cndmask_b32_e64 v65, v57, v61, s[20:21]
	v_cndmask_b32_e64 v64, v64, v60, s[22:23]
	v_pk_mul_f32 v[60:61], v[40:41], v[64:65]
	v_pk_mul_f32 v[64:65], v[36:37], v[64:65]
	v_pk_fma_f32 v[62:63], v[38:39], v[62:63], v[72:73] neg_lo:[0,0,1] neg_hi:[0,0,1]
	v_pk_fma_f32 v[60:61], v[36:37], v[66:67], v[60:61]
	v_pk_fma_f32 v[64:65], v[40:41], v[66:67], v[64:65] neg_lo:[0,0,1] neg_hi:[0,0,1]
	v_lshl_add_u64 v[66:67], v[70:71], 0, v[134:135]
	v_lshlrev_b32_e32 v134, 1, v136
	global_store_dwordx4 v[66:67], v[62:65], off
	global_store_dwordx4 v[66:67], v[58:61], off offset:64
	s_nop 0
	v_cvt_pk_bf16_f32 v62, v62, v63
	v_cvt_pk_bf16_f32 v63, v64, v65
	s_nop 0
	v_cvt_pk_bf16_f32 v58, v58, v59
	v_cvt_pk_bf16_f32 v59, v60, v61
	v_lshl_add_u64 v[60:61], v[74:75], 0, v[134:135]
	global_store_dwordx2 v[60:61], v[62:63], off offset:256
	global_store_dwordx2 v[60:61], v[58:59], off offset:288

.LBB0_467:
	s_or_b64 exec, exec, s[14:15]
	s_andn2_b64 vcc, exec, s[40:41]
	s_cbranch_vccnz .LBB0_469
	s_waitcnt lgkmcnt(0)
	v_mov_b32_e32 v42, v246
	v_mov_b32_e32 v43, v247
	v_mov_b32_e32 v44, v248
	v_mov_b32_e32 v45, v249
	v_readlane_b32 s14, v255, 0
	v_and_b32_e32 v41, 0x1fef, v34
	v_cmp_gt_i32_e32 vcc, s77, v34
	v_readlane_b32 s15, v255, 1
	s_load_dwordx4 s[0:3], s[14:15], 0x108
	v_cndmask_b32_e32 v41, v158, v41, vcc
	v_cvt_f32_u32_e32 v56, v41
	v_add_u32_e32 v134, 0xffffc0a0, v154
	v_lshlrev_b64 v[46:47], 7, v[34:35]
	v_mov_b32_e32 v49, v135
	v_lshlrev_b64 v[54:55], 7, v[134:135]
	v_cndmask_b32_e32 v48, v164, v165, vcc
	v_cndmask_b32_e32 v57, 0, v35, vcc
	v_lshl_add_u64 v[46:47], s[46:47], 0, v[46:47]
	v_cndmask_b32_e32 v58, v134, v34, vcc
	v_lshl_add_u64 v[54:55], s[44:45], 0, v[54:55]
	s_waitcnt lgkmcnt(0)
	v_lshl_add_u64 v[48:49], s[2:3], 0, v[48:49]
	v_cndmask_b32_e32 v55, v55, v47, vcc
	v_cndmask_b32_e32 v54, v54, v46, vcc
	v_mad_u64_u32 v[58:59], s[0:1], v58, s95, v[48:49]
	v_mad_i32_i24 v59, v57, s95, v59
	v_mov_b64_e32 v[50:51], s[54:55]
	v_mov_b64_e32 v[52:53], s[62:63]
	v_lshlrev_b32_e32 v134, 2, v136
	v_pk_mul_f32 v[42:43], v[42:43], v[56:57] op_sel_hi:[1,0]
	v_pk_mul_f32 v[44:45], v[44:45], v[56:57] op_sel_hi:[1,0]
	v_cvt_f64_f32_e32 v[46:47], v42
	v_cvt_f64_f32_e32 v[42:43], v43
	v_cvt_f64_f32_e32 v[48:49], v44
	v_cvt_f64_f32_e32 v[44:45], v45
	v_mul_f64 v[56:57], v[42:43], s[48:49]
	v_mul_f64 v[60:61], v[46:47], s[48:49]
	v_mul_f64 v[62:63], v[44:45], s[48:49]
	v_mul_f64 v[64:65], v[48:49], s[48:49]
	v_rndne_f64_e32 v[60:61], v[60:61]
	v_rndne_f64_e32 v[56:57], v[56:57]
	v_rndne_f64_e32 v[64:65], v[64:65]
	v_rndne_f64_e32 v[62:63], v[62:63]
	v_fma_f64 v[42:43], v[42:43], s[48:49], -v[56:57]
	v_fma_f64 v[46:47], v[46:47], s[48:49], -v[60:61]
	v_fma_f64 v[44:45], v[44:45], s[48:49], -v[62:63]
	v_fma_f64 v[48:49], v[48:49], s[48:49], -v[64:65]
	v_mul_f64 v[46:47], v[46:47], s[50:51]
	v_mul_f64 v[42:43], v[42:43], s[50:51]
	v_mul_f64 v[48:49], v[48:49], s[50:51]
	v_mul_f64 v[44:45], v[44:45], s[50:51]
	v_cvt_f32_f64_e32 v43, v[42:43]
	v_cvt_f32_f64_e32 v42, v[46:47]
	v_cvt_i32_f64_e32 v41, v[56:57]
	v_cvt_i32_f64_e32 v56, v[60:61]
	v_cvt_i32_f64_e32 v57, v[62:63]
	v_cvt_i32_f64_e32 v60, v[64:65]
	v_cvt_f32_f64_e32 v45, v[44:45]
	v_cvt_f32_f64_e32 v44, v[48:49]
	v_pk_mul_f32 v[46:47], v[42:43], v[42:43]
	v_and_b32_e32 v62, 3, v56
	v_and_b32_e32 v63, 3, v57
	v_and_b32_e32 v64, 3, v60
	v_pk_mul_f32 v[48:49], v[44:45], v[44:45]
	v_pk_fma_f32 v[56:57], v[46:47], s[52:53], v[50:51] op_sel_hi:[1,0,0]
	v_pk_fma_f32 v[60:61], v[46:47], s[60:61], v[52:53] op_sel_hi:[1,0,0] neg_lo:[1,0,0] neg_hi:[1,0,0]
	v_pk_fma_f32 v[50:51], v[48:49], s[52:53], v[50:51] op_sel_hi:[1,0,0]
	v_pk_fma_f32 v[56:57], v[46:47], v[56:57], s[56:57] op_sel_hi:[1,1,0]
	v_pk_fma_f32 v[60:61], v[46:47], v[60:61], s[64:65] op_sel_hi:[1,1,0]
	v_pk_fma_f32 v[50:51], v[48:49], v[50:51], s[56:57] op_sel_hi:[1,1,0]
	v_pk_fma_f32 v[56:57], v[46:47], v[56:57], s[58:59] op_sel_hi:[1,1,0]
	v_pk_fma_f32 v[60:61], v[46:47], v[60:61], s[66:67] op_sel_hi:[1,1,0]
	v_and_b32_e32 v41, 3, v41
	v_pk_fma_f32 v[50:51], v[48:49], v[50:51], s[58:59] op_sel_hi:[1,1,0]
	v_pk_fma_f32 v[56:57], v[46:47], v[56:57], 1.0 op_sel_hi:[1,1,0]
	v_pk_fma_f32 v[60:61], v[46:47], v[60:61], -0.5 op_sel_hi:[1,1,0]
	v_pk_fma_f32 v[50:51], v[48:49], v[50:51], 1.0 op_sel_hi:[1,1,0]
	v_pk_mul_f32 v[42:43], v[56:57], v[42:43]
	v_pk_fma_f32 v[46:47], v[46:47], v[60:61], 1.0 op_sel_hi:[1,1,0]
	v_cmp_eq_u32_e32 vcc, 2, v41
	v_cmp_eq_u32_e64 s[14:15], 2, v62
	v_pk_mul_f32 v[44:45], v[50:51], v[44:45]
	v_cndmask_b32_e64 v50, v43, -v47, vcc
	v_cndmask_b32_e64 v51, v42, -v46, s[14:15]
	v_cndmask_b32_e32 v56, v47, v43, vcc
	v_cndmask_b32_e64 v57, v46, v42, s[14:15]
	v_cmp_eq_u32_e32 vcc, 1, v62
	v_cmp_eq_u32_e64 s[14:15], 1, v41
	v_pk_fma_f32 v[52:53], v[48:49], s[60:61], v[52:53] op_sel_hi:[1,0,0] neg_lo:[1,0,0] neg_hi:[1,0,0]
	v_cndmask_b32_e64 v51, v51, -v42, vcc
	v_cndmask_b32_e64 v50, v50, -v43, s[14:15]
	v_cndmask_b32_e64 v57, -v57, v46, vcc
	v_cndmask_b32_e64 v56, -v56, v47, s[14:15]
	v_cmp_eq_u32_e32 vcc, 0, v41
	v_cmp_eq_u32_e64 s[14:15], 0, v62
	v_pk_fma_f32 v[52:53], v[48:49], v[52:53], s[64:65] op_sel_hi:[1,1,0]
	v_cndmask_b32_e32 v43, v56, v43, vcc
	v_cndmask_b32_e64 v42, v57, v42, s[14:15]
	v_pk_fma_f32 v[52:53], v[48:49], v[52:53], s[66:67] op_sel_hi:[1,1,0]
	v_cndmask_b32_e32 v47, v50, v47, vcc
	v_cndmask_b32_e64 v46, v51, v46, s[14:15]
	v_pk_mul_f32 v[50:51], v[22:23], v[42:43]
	v_pk_mul_f32 v[56:57], v[18:19], v[42:43]
	v_pk_fma_f32 v[42:43], v[18:19], v[46:47], v[50:51]
	v_pk_fma_f32 v[50:51], v[48:49], v[52:53], -0.5 op_sel_hi:[1,1,0]
	v_cmp_eq_u32_e32 vcc, 2, v63
	v_pk_fma_f32 v[48:49], v[48:49], v[50:51], 1.0 op_sel_hi:[1,1,0]
	v_cmp_eq_u32_e64 s[14:15], 2, v64
	v_cndmask_b32_e64 v41, v45, -v49, vcc
	v_cmp_eq_u32_e64 s[18:19], 1, v63
	v_cndmask_b32_e64 v50, v44, -v48, s[14:15]
	v_cmp_eq_u32_e64 s[16:17], 1, v64
	v_cndmask_b32_e64 v41, v41, -v45, s[18:19]
	v_cmp_eq_u32_e64 s[20:21], 0, v63
	v_cndmask_b32_e64 v50, v50, -v44, s[16:17]
	v_cmp_eq_u32_e64 s[22:23], 0, v64
	v_cndmask_b32_e64 v51, v41, v49, s[20:21]
	v_cndmask_b32_e32 v41, v49, v45, vcc
	v_cndmask_b32_e64 v52, v48, v44, s[14:15]
	v_cndmask_b32_e64 v50, v50, v48, s[22:23]
	v_cndmask_b32_e64 v48, -v52, v48, s[16:17]
	v_cndmask_b32_e64 v41, -v41, v49, s[18:19]
	v_cndmask_b32_e64 v49, v41, v45, s[20:21]
	v_cndmask_b32_e64 v48, v48, v44, s[22:23]
	v_pk_mul_f32 v[44:45], v[24:25], v[48:49]
	v_pk_mul_f32 v[48:49], v[20:21], v[48:49]
	v_pk_fma_f32 v[46:47], v[22:23], v[46:47], v[56:57] neg_lo:[0,0,1] neg_hi:[0,0,1]
	v_pk_fma_f32 v[44:45], v[20:21], v[50:51], v[44:45]
	v_pk_fma_f32 v[48:49], v[24:25], v[50:51], v[48:49] neg_lo:[0,0,1] neg_hi:[0,0,1]
	v_lshl_add_u64 v[50:51], v[54:55], 0, v[134:135]
	v_lshlrev_b32_e32 v134, 1, v136
	global_store_dwordx4 v[50:51], v[46:49], off
	global_store_dwordx4 v[50:51], v[42:45], off offset:64
	s_nop 0
	v_cvt_pk_bf16_f32 v46, v46, v47
	v_cvt_pk_bf16_f32 v47, v48, v49
	s_nop 0
	v_cvt_pk_bf16_f32 v42, v42, v43
	v_cvt_pk_bf16_f32 v43, v44, v45
	v_lshl_add_u64 v[44:45], v[58:59], 0, v[134:135]
	global_store_dwordx2 v[44:45], v[46:47], off offset:256
	global_store_dwordx2 v[44:45], v[42:43], off offset:288

.LBB0_489:
	s_or_b64 exec, exec, s[10:11]
	s_andn2_b64 vcc, exec, s[40:41]
	s_cbranch_vccnz .LBB0_491
	s_waitcnt lgkmcnt(0)
	v_mov_b32_e32 v26, v246
	v_mov_b32_e32 v27, v247
	v_mov_b32_e32 v28, v248
	v_mov_b32_e32 v29, v249
	v_readlane_b32 s10, v255, 0
	v_and_b32_e32 v25, 0x1fff, v18
	v_cmp_gt_i32_e32 vcc, s77, v18
	v_readlane_b32 s11, v255, 1
	s_load_dwordx4 s[0:3], s[10:11], 0x108
	v_cndmask_b32_e32 v25, v158, v25, vcc
	v_cvt_f32_u32_e32 v40, v25
	v_add_u32_e32 v134, 0xffffc0b0, v154
	v_lshlrev_b64 v[30:31], 7, v[18:19]
	v_mov_b32_e32 v33, v135
	v_lshlrev_b64 v[38:39], 7, v[134:135]
	v_cndmask_b32_e32 v32, v164, v165, vcc
	v_cndmask_b32_e32 v41, 0, v19, vcc
	v_lshl_add_u64 v[30:31], s[46:47], 0, v[30:31]
	v_cndmask_b32_e32 v42, v134, v18, vcc
	v_lshl_add_u64 v[38:39], s[44:45], 0, v[38:39]
	s_waitcnt lgkmcnt(0)
	v_lshl_add_u64 v[32:33], s[2:3], 0, v[32:33]
	v_cndmask_b32_e32 v39, v39, v31, vcc
	v_cndmask_b32_e32 v38, v38, v30, vcc
	v_mad_u64_u32 v[42:43], s[0:1], v42, s95, v[32:33]
	v_mad_i32_i24 v43, v41, s95, v43
	v_mov_b64_e32 v[34:35], s[54:55]
	v_mov_b64_e32 v[36:37], s[62:63]
	v_lshlrev_b32_e32 v134, 2, v136
	v_pk_mul_f32 v[26:27], v[26:27], v[40:41] op_sel_hi:[1,0]
	v_pk_mul_f32 v[28:29], v[28:29], v[40:41] op_sel_hi:[1,0]
	v_cvt_f64_f32_e32 v[30:31], v26
	v_cvt_f64_f32_e32 v[26:27], v27
	v_cvt_f64_f32_e32 v[32:33], v28
	v_cvt_f64_f32_e32 v[28:29], v29
	v_mul_f64 v[40:41], v[26:27], s[48:49]
	v_mul_f64 v[44:45], v[30:31], s[48:49]
	v_mul_f64 v[46:47], v[28:29], s[48:49]
	v_mul_f64 v[48:49], v[32:33], s[48:49]
	v_rndne_f64_e32 v[44:45], v[44:45]
	v_rndne_f64_e32 v[40:41], v[40:41]
	v_rndne_f64_e32 v[48:49], v[48:49]
	v_rndne_f64_e32 v[46:47], v[46:47]
	v_fma_f64 v[26:27], v[26:27], s[48:49], -v[40:41]
	v_fma_f64 v[30:31], v[30:31], s[48:49], -v[44:45]
	v_fma_f64 v[28:29], v[28:29], s[48:49], -v[46:47]
	v_fma_f64 v[32:33], v[32:33], s[48:49], -v[48:49]
	v_mul_f64 v[30:31], v[30:31], s[50:51]
	v_mul_f64 v[26:27], v[26:27], s[50:51]
	v_mul_f64 v[32:33], v[32:33], s[50:51]
	v_mul_f64 v[28:29], v[28:29], s[50:51]
	v_cvt_f32_f64_e32 v27, v[26:27]
	v_cvt_f32_f64_e32 v26, v[30:31]
	v_cvt_i32_f64_e32 v25, v[40:41]
	v_cvt_i32_f64_e32 v40, v[44:45]
	v_cvt_i32_f64_e32 v41, v[46:47]
	v_cvt_i32_f64_e32 v44, v[48:49]
	v_cvt_f32_f64_e32 v29, v[28:29]
	v_cvt_f32_f64_e32 v28, v[32:33]
	v_pk_mul_f32 v[30:31], v[26:27], v[26:27]
	v_and_b32_e32 v46, 3, v40
	v_and_b32_e32 v47, 3, v41
	v_and_b32_e32 v48, 3, v44
	v_pk_mul_f32 v[32:33], v[28:29], v[28:29]
	v_pk_fma_f32 v[40:41], v[30:31], s[52:53], v[34:35] op_sel_hi:[1,0,0]
	v_pk_fma_f32 v[44:45], v[30:31], s[60:61], v[36:37] op_sel_hi:[1,0,0] neg_lo:[1,0,0] neg_hi:[1,0,0]
	v_pk_fma_f32 v[34:35], v[32:33], s[52:53], v[34:35] op_sel_hi:[1,0,0]
	v_pk_fma_f32 v[40:41], v[30:31], v[40:41], s[56:57] op_sel_hi:[1,1,0]
	v_pk_fma_f32 v[44:45], v[30:31], v[44:45], s[64:65] op_sel_hi:[1,1,0]
	v_pk_fma_f32 v[34:35], v[32:33], v[34:35], s[56:57] op_sel_hi:[1,1,0]
	v_pk_fma_f32 v[40:41], v[30:31], v[40:41], s[58:59] op_sel_hi:[1,1,0]
	v_pk_fma_f32 v[44:45], v[30:31], v[44:45], s[66:67] op_sel_hi:[1,1,0]
	v_and_b32_e32 v25, 3, v25
	v_pk_fma_f32 v[34:35], v[32:33], v[34:35], s[58:59] op_sel_hi:[1,1,0]
	v_pk_fma_f32 v[40:41], v[30:31], v[40:41], 1.0 op_sel_hi:[1,1,0]
	v_pk_fma_f32 v[44:45], v[30:31], v[44:45], -0.5 op_sel_hi:[1,1,0]
	v_pk_fma_f32 v[34:35], v[32:33], v[34:35], 1.0 op_sel_hi:[1,1,0]
	v_pk_mul_f32 v[26:27], v[40:41], v[26:27]
	v_pk_fma_f32 v[30:31], v[30:31], v[44:45], 1.0 op_sel_hi:[1,1,0]
	v_cmp_eq_u32_e32 vcc, 2, v25
	v_cmp_eq_u32_e64 s[10:11], 2, v46
	v_pk_mul_f32 v[28:29], v[34:35], v[28:29]
	v_cndmask_b32_e64 v34, v27, -v31, vcc
	v_cndmask_b32_e64 v35, v26, -v30, s[10:11]
	v_cndmask_b32_e32 v40, v31, v27, vcc
	v_cndmask_b32_e64 v41, v30, v26, s[10:11]
	v_cmp_eq_u32_e32 vcc, 1, v46
	v_cmp_eq_u32_e64 s[10:11], 1, v25
	v_pk_fma_f32 v[36:37], v[32:33], s[60:61], v[36:37] op_sel_hi:[1,0,0] neg_lo:[1,0,0] neg_hi:[1,0,0]
	v_cndmask_b32_e64 v35, v35, -v26, vcc
	v_cndmask_b32_e64 v34, v34, -v27, s[10:11]
	v_cndmask_b32_e64 v41, -v41, v30, vcc
	v_cndmask_b32_e64 v40, -v40, v31, s[10:11]
	v_cmp_eq_u32_e32 vcc, 0, v25
	v_cmp_eq_u32_e64 s[10:11], 0, v46
	v_pk_fma_f32 v[36:37], v[32:33], v[36:37], s[64:65] op_sel_hi:[1,1,0]
	v_cndmask_b32_e32 v27, v40, v27, vcc
	v_cndmask_b32_e64 v26, v41, v26, s[10:11]
	v_pk_fma_f32 v[36:37], v[32:33], v[36:37], s[66:67] op_sel_hi:[1,1,0]
	v_cndmask_b32_e32 v31, v34, v31, vcc
	v_cndmask_b32_e64 v30, v35, v30, s[10:11]
	v_pk_mul_f32 v[34:35], v[6:7], v[26:27]
	v_pk_mul_f32 v[40:41], v[2:3], v[26:27]
	v_pk_fma_f32 v[26:27], v[2:3], v[30:31], v[34:35]
	v_pk_fma_f32 v[34:35], v[32:33], v[36:37], -0.5 op_sel_hi:[1,1,0]
	v_cmp_eq_u32_e32 vcc, 2, v47
	v_pk_fma_f32 v[32:33], v[32:33], v[34:35], 1.0 op_sel_hi:[1,1,0]
	v_cmp_eq_u32_e64 s[10:11], 2, v48
	v_cndmask_b32_e64 v25, v29, -v33, vcc
	v_cmp_eq_u32_e64 s[14:15], 1, v47
	v_cndmask_b32_e64 v34, v28, -v32, s[10:11]
	v_cmp_eq_u32_e64 s[12:13], 1, v48
	v_cndmask_b32_e64 v25, v25, -v29, s[14:15]
	v_cmp_eq_u32_e64 s[16:17], 0, v47
	v_cndmask_b32_e64 v34, v34, -v28, s[12:13]
	v_cmp_eq_u32_e64 s[18:19], 0, v48
	v_cndmask_b32_e64 v35, v25, v33, s[16:17]
	v_cndmask_b32_e32 v25, v33, v29, vcc
	v_cndmask_b32_e64 v36, v32, v28, s[10:11]
	v_cndmask_b32_e64 v34, v34, v32, s[18:19]
	v_cndmask_b32_e64 v32, -v36, v32, s[12:13]
	v_cndmask_b32_e64 v25, -v25, v33, s[14:15]
	v_cndmask_b32_e64 v33, v25, v29, s[16:17]
	v_cndmask_b32_e64 v32, v32, v28, s[18:19]
	v_pk_mul_f32 v[28:29], v[8:9], v[32:33]
	v_pk_mul_f32 v[32:33], v[4:5], v[32:33]
	v_pk_fma_f32 v[30:31], v[6:7], v[30:31], v[40:41] neg_lo:[0,0,1] neg_hi:[0,0,1]
	v_pk_fma_f32 v[28:29], v[4:5], v[34:35], v[28:29]
	v_pk_fma_f32 v[32:33], v[8:9], v[34:35], v[32:33] neg_lo:[0,0,1] neg_hi:[0,0,1]
	v_lshl_add_u64 v[34:35], v[38:39], 0, v[134:135]
	v_lshlrev_b32_e32 v134, 1, v136
	global_store_dwordx4 v[34:35], v[30:33], off
	global_store_dwordx4 v[34:35], v[26:29], off offset:64
	s_nop 0
	v_cvt_pk_bf16_f32 v30, v30, v31
	v_cvt_pk_bf16_f32 v31, v32, v33
	s_nop 0
	v_cvt_pk_bf16_f32 v26, v26, v27
	v_cvt_pk_bf16_f32 v27, v28, v29
	v_lshl_add_u64 v[28:29], v[42:43], 0, v[134:135]
	global_store_dwordx2 v[28:29], v[30:31], off offset:256
	global_store_dwordx2 v[28:29], v[26:27], off offset:288
